# ret_out: four 16-line touch loads of the unit's RS block issued behind the staging loads (counted waits shifted by 4) so the RS fragment loads hit L2
# baseline (speedup 1.0000x reference)
.LBB0_490:
	s_or_b64 exec, exec, s[0:1]
	v_lshlrev_b32_e32 v70, 7, v6
	v_lshlrev_b32_e32 v2, 3, v5
	v_ashrrev_i32_e32 v71, 31, v70
	v_and_b32_e32 v7, 56, v2
	v_bfe_u32 v13, v5, 3, 5
	v_lshlrev_b64 v[72:73], 1, v[70:71]
	v_lshlrev_b32_e32 v0, 3, v7
	v_mov_b32_e32 v1, v65
	v_or_b32_e32 v8, v3, v13
	v_lshl_add_u64 v[0:1], s[40:41], 0, v[0:1]
	v_lshlrev_b32_e32 v8, 9, v8
	v_mov_b32_e32 v9, v65
	v_lshl_add_u64 v[18:19], s[38:39], 0, v[72:73]
	v_lshlrev_b32_e32 v64, 1, v7
	v_lshl_add_u64 v[38:39], v[0:1], 0, v[8:9]
	v_lshl_add_u64 v[42:43], v[18:19], 0, v[64:65]
	v_add_u32_e32 v7, v68, v13
	global_load_dwordx4 v[8:11], v[38:39], off
	global_load_dwordx4 v[14:17], v[38:39], off offset:16
	global_load_dwordx4 v[18:21], v[38:39], off offset:32
	v_mad_i64_i32 v[34:35], s[0:1], v7, s57, v[42:43]
	global_load_dwordx4 v[22:25], v[34:35], off
	global_load_dwordx4 v[26:29], v[34:35], off offset:128
	global_load_dwordx4 v[30:33], v[34:35], off offset:1536
	s_nop 0
	global_load_dwordx4 v[34:37], v[34:35], off offset:1664
	s_nop 0
	global_load_dwordx4 v[38:41], v[38:39], off offset:48
	v_or_b32_sdwa v140, v5, s61 dst_sel:DWORD dst_unused:UNUSED_PAD src0_sel:BYTE_0 src1_sel:DWORD
	v_lshrrev_b32_e32 v141, 3, v140
	v_add_u32_e32 v142, v68, v141
	v_mad_i64_i32 v[134:135], s[0:1], v142, s57, v[42:43]
	v_or_b32_e32 v143, v3, v141
	v_lshlrev_b32_e32 v136, 9, v143
	v_mov_b32_e32 v137, v65
	v_lshl_add_u64 v[136:137], v[0:1], 0, v[136:137]
	global_load_dwordx4 v[160:163], v[134:135], off
	global_load_dwordx4 v[164:167], v[134:135], off offset:128
	global_load_dwordx4 v[168:171], v[134:135], off offset:1536
	global_load_dwordx4 v[172:175], v[134:135], off offset:1664
	global_load_dwordx4 v[176:179], v[136:137], off
	global_load_dwordx4 v[180:183], v[136:137], off offset:16
	global_load_dwordx4 v[184:187], v[136:137], off offset:32
	global_load_dwordx4 v[188:191], v[136:137], off offset:48
	v_bfe_u32 v140, v5, 4, 4
	v_add_u32_e32 v140, v68, v140
	v_mad_i64_i32 v[138:139], s[0:1], v140, s57, v[66:67]
	v_lshl_add_u64 v[138:139], v[138:139], 0, v[72:73]
	v_lshlrev_b32_e32 v140, 3, v5
	v_and_b32_e32 v140, 0x78, v140
	v_lshlrev_b32_e32 v140, 1, v140
	v_mov_b32_e32 v141, v65
	v_lshl_add_u64 v[138:139], v[138:139], 0, v[140:141]
	v_mov_b32_e32 v140, 0x1a000
	global_load_dwordx4 v[192:195], v[138:139], off offset:3072
	v_lshl_add_u64 v[138:139], v[138:139], 0, v[140:141]
	global_load_dwordx4 v[196:199], v[138:139], off offset:3072
	v_lshl_add_u64 v[138:139], v[138:139], 0, v[140:141]
	global_load_dwordx4 v[200:203], v[138:139], off offset:3072
	v_lshl_add_u64 v[138:139], v[138:139], 0, v[140:141]
	global_load_dwordx4 v[204:207], v[138:139], off offset:3072
	v_bfe_u32 v252, v154, 6, 2
	v_lshlrev_b32_e32 v252, 13, v252
	v_lshl_add_u32 v252, v12, 15, v252
	v_and_b32_e32 v253, 15, v154
	v_lshl_add_u32 v252, v253, 7, v252
	v_bfe_u32 v253, v154, 4, 2
	v_lshl_add_u32 v252, v253, 2, v252
	v_add_u32_e32 v253, 0x1000, v252
	global_load_dword v133, v252, s[42:43]
	global_load_dword v144, v252, s[42:43] offset:2048
	global_load_dword v159, v253, s[42:43]
	global_load_dword v149, v253, s[42:43] offset:2048
	v_mul_u32_u24_e32 v7, 0x88, v13
	v_mad_i32_i24 v4, v4, s52, 0
	v_lshlrev_b32_e32 v7, 1, v7
	v_add3_u32 v7, v4, v7, v64
	s_add_i32 s2, s2, s84
	s_waitcnt vmcnt(16) lgkmcnt(0)
	v_mov_b32_e32 v44, v8
	v_mov_b32_e32 v45, v10
	v_mov_b32_e32 v10, v9
	v_mov_b32_e32 v8, v14
	v_mov_b32_e32 v9, v16
	v_mov_b32_e32 v16, v15
	v_mov_b32_e32 v14, v18
	v_mov_b32_e32 v15, v20
	v_mov_b32_e32 v20, v19
	v_lshlrev_b32_e32 v18, 16, v22
	v_and_b32_e32 v19, 0xffff0000, v22
	v_lshlrev_b32_e32 v22, 16, v23
	v_and_b32_e32 v23, 0xffff0000, v23
	v_lshlrev_b32_e32 v48, 16, v26
	v_and_b32_e32 v49, 0xffff0000, v26
	v_lshlrev_b32_e32 v26, 16, v27
	v_and_b32_e32 v27, 0xffff0000, v27
	v_lshlrev_b32_e32 v52, 16, v30
	v_and_b32_e32 v53, 0xffff0000, v30
	v_lshlrev_b32_e32 v30, 16, v31
	v_and_b32_e32 v31, 0xffff0000, v31
	v_lshlrev_b32_e32 v56, 16, v34
	v_and_b32_e32 v57, 0xffff0000, v34
	v_lshlrev_b32_e32 v34, 16, v35
	v_and_b32_e32 v35, 0xffff0000, v35
	v_pk_mul_f32 v[76:77], v[16:17], v[26:27]
	v_pk_mul_f32 v[84:85], v[16:17], v[22:23]
	v_pk_mul_f32 v[86:87], v[16:17], v[34:35]
	v_pk_mul_f32 v[16:17], v[16:17], v[30:31]
	v_lshlrev_b32_e32 v46, 16, v24
	v_and_b32_e32 v47, 0xffff0000, v24
	v_lshlrev_b32_e32 v50, 16, v28
	v_and_b32_e32 v51, 0xffff0000, v28
	v_pk_mul_f32 v[60:61], v[10:11], v[48:49]
	v_pk_mul_f32 v[62:63], v[10:11], v[18:19]
	v_pk_mul_f32 v[74:75], v[10:11], v[56:57]
	v_pk_mul_f32 v[10:11], v[10:11], v[52:53]
	v_pk_fma_f32 v[22:23], v[8:9], v[22:23], v[76:77] neg_lo:[0,0,1] neg_hi:[0,0,1]
	v_pk_fma_f32 v[26:27], v[8:9], v[26:27], v[84:85]
	v_pk_fma_f32 v[30:31], v[8:9], v[30:31], v[86:87] neg_lo:[0,0,1] neg_hi:[0,0,1]
	v_pk_fma_f32 v[8:9], v[8:9], v[34:35], v[16:17]
	v_lshlrev_b32_e32 v58, 16, v36
	v_and_b32_e32 v59, 0xffff0000, v36
	v_pk_mul_f32 v[88:89], v[20:21], v[50:51]
	v_pk_fma_f32 v[18:19], v[44:45], v[18:19], v[60:61] neg_lo:[0,0,1] neg_hi:[0,0,1]
	v_pk_fma_f32 v[48:49], v[44:45], v[48:49], v[62:63]
	v_pk_fma_f32 v[52:53], v[44:45], v[52:53], v[74:75] neg_lo:[0,0,1] neg_hi:[0,0,1]
	v_pk_fma_f32 v[10:11], v[44:45], v[56:57], v[10:11]
	v_pk_mul_f32 v[44:45], v[8:9], s[44:45] op_sel_hi:[1,0]
	v_pk_mul_f32 v[8:9], v[20:21], v[46:47]
	v_lshlrev_b32_e32 v54, 16, v32
	v_and_b32_e32 v55, 0xffff0000, v32
	v_pk_mul_f32 v[34:35], v[10:11], s[44:45] op_sel_hi:[1,0]
	v_pk_fma_f32 v[10:11], v[14:15], v[46:47], v[88:89] neg_lo:[0,0,1] neg_hi:[0,0,1]
	v_pk_fma_f32 v[46:47], v[14:15], v[50:51], v[8:9]
	v_pk_mul_f32 v[8:9], v[20:21], v[58:59]
	v_lshlrev_b32_e32 v28, 16, v29
	v_pk_fma_f32 v[8:9], v[14:15], v[54:55], v[8:9] neg_lo:[0,0,1] neg_hi:[0,0,1]
	v_and_b32_e32 v29, 0xffff0000, v29
	v_pk_mul_f32 v[50:51], v[8:9], s[44:45] op_sel_hi:[1,0]
	v_pk_mul_f32 v[8:9], v[20:21], v[54:55]
	v_lshlrev_b32_e32 v24, 16, v25
	v_pk_fma_f32 v[8:9], v[14:15], v[58:59], v[8:9]
	v_and_b32_e32 v25, 0xffff0000, v25
	v_pk_mul_f32 v[14:15], v[8:9], s[44:45] op_sel_hi:[1,0]
	v_mov_b32_e32 v9, v40
	v_mov_b32_e32 v40, v39
	v_mov_b32_e32 v8, v38
	v_pk_mul_f32 v[20:21], v[40:41], v[28:29]
	v_lshlrev_b32_e32 v36, 16, v37
	v_and_b32_e32 v37, 0xffff0000, v37
	v_pk_fma_f32 v[20:21], v[8:9], v[24:25], v[20:21] neg_lo:[0,0,1] neg_hi:[0,0,1]
	v_pk_mul_f32 v[24:25], v[40:41], v[24:25]
	v_lshlrev_b32_e32 v32, 16, v33
	v_and_b32_e32 v33, 0xffff0000, v33
	v_pk_fma_f32 v[24:25], v[8:9], v[28:29], v[24:25]
	v_pk_mul_f32 v[28:29], v[40:41], v[36:37]
	v_cvt_pk_bf16_f32 v10, v10, v11
	v_pk_fma_f32 v[28:29], v[8:9], v[32:33], v[28:29] neg_lo:[0,0,1] neg_hi:[0,0,1]
	v_pk_mul_f32 v[32:33], v[40:41], v[32:33]
	v_cvt_pk_bf16_f32 v11, v20, v21
	v_pk_fma_f32 v[8:9], v[8:9], v[36:37], v[32:33]
	v_pk_mul_f32 v[16:17], v[52:53], s[44:45] op_sel_hi:[1,0]
	v_pk_mul_f32 v[32:33], v[8:9], s[44:45] op_sel_hi:[1,0]
	v_cvt_pk_bf16_f32 v8, v18, v19
	v_cvt_pk_bf16_f32 v9, v22, v23
	v_pk_mul_f32 v[30:31], v[30:31], s[44:45] op_sel_hi:[1,0]
	v_pk_mul_f32 v[28:29], v[28:29], s[44:45] op_sel_hi:[1,0]
	ds_write_b128 v7, v[8:11]
	v_cvt_pk_bf16_f32 v8, v48, v49
	v_cvt_pk_bf16_f32 v9, v26, v27
	v_cvt_pk_bf16_f32 v10, v46, v47
	v_cvt_pk_bf16_f32 v11, v24, v25
	ds_write_b128 v7, v[8:11] offset:128
	v_cvt_pk_bf16_f32 v8, v16, v17
	v_cvt_pk_bf16_f32 v9, v30, v31
	v_cvt_pk_bf16_f32 v10, v50, v51
	v_cvt_pk_bf16_f32 v11, v28, v29
	ds_write_b128 v7, v[8:11] offset:17408
	v_cvt_pk_bf16_f32 v8, v34, v35
	v_cvt_pk_bf16_f32 v9, v44, v45
	v_cvt_pk_bf16_f32 v10, v14, v15
	v_cvt_pk_bf16_f32 v11, v32, v33
	ds_write_b128 v7, v[8:11] offset:17536
	v_or_b32_sdwa v7, v5, s61 dst_sel:DWORD dst_unused:UNUSED_PAD src0_sel:BYTE_0 src1_sel:DWORD
	v_lshrrev_b32_e32 v13, 3, v7
	v_add_u32_e32 v8, v68, v13
	v_or_b32_e32 v3, v3, v13
	v_mad_i64_i32 v[22:23], s[0:1], v8, s57, v[42:43]
	v_lshlrev_b32_e32 v26, 9, v3
	v_mov_b32_e32 v27, v65
	s_nop 0
	v_lshl_add_u64 v[0:1], v[0:1], 0, v[26:27]
	v_mul_u32_u24_e32 v3, 0x88, v13
	v_lshlrev_b32_e32 v3, 1, v3
	v_add3_u32 v3, v4, v3, v64
	v_lshrrev_b32_e32 v7, 4, v7
	s_waitcnt vmcnt(8) lgkmcnt(0)
	v_mov_b64_e32 v[8:9], v[160:161]
	v_mov_b64_e32 v[10:11], v[162:163]
	v_mov_b64_e32 v[14:15], v[164:165]
	v_mov_b64_e32 v[16:17], v[166:167]
	v_mov_b64_e32 v[18:19], v[168:169]
	v_mov_b64_e32 v[20:21], v[170:171]
	v_mov_b64_e32 v[22:23], v[172:173]
	v_mov_b64_e32 v[24:25], v[174:175]
	v_mov_b64_e32 v[26:27], v[176:177]
	v_mov_b64_e32 v[28:29], v[178:179]
	v_mov_b64_e32 v[30:31], v[180:181]
	v_mov_b64_e32 v[32:33], v[182:183]
	v_mov_b64_e32 v[34:35], v[184:185]
	v_mov_b64_e32 v[36:37], v[186:187]
	v_mov_b64_e32 v[38:39], v[188:189]
	v_mov_b64_e32 v[40:41], v[190:191]
	v_lshlrev_b32_e32 v0, 16, v8
	v_lshlrev_b32_e32 v44, 16, v14
	v_and_b32_e32 v45, 0xffff0000, v14
	v_mov_b32_e32 v57, v28
	v_mov_b32_e32 v28, v27
	v_and_b32_e32 v1, 0xffff0000, v8
	v_mov_b32_e32 v56, v26
	v_pk_mul_f32 v[26:27], v[28:29], v[44:45]
	v_lshlrev_b32_e32 v52, 16, v22
	v_and_b32_e32 v53, 0xffff0000, v22
	v_pk_fma_f32 v[26:27], v[56:57], v[0:1], v[26:27] neg_lo:[0,0,1] neg_hi:[0,0,1]
	v_pk_mul_f32 v[0:1], v[28:29], v[0:1]
	v_lshlrev_b32_e32 v48, 16, v18
	v_and_b32_e32 v49, 0xffff0000, v18
	v_pk_fma_f32 v[0:1], v[56:57], v[44:45], v[0:1]
	v_pk_mul_f32 v[44:45], v[28:29], v[52:53]
	v_lshlrev_b32_e32 v14, 16, v15
	v_and_b32_e32 v15, 0xffff0000, v15
	v_pk_fma_f32 v[44:45], v[56:57], v[48:49], v[44:45] neg_lo:[0,0,1] neg_hi:[0,0,1]
	v_pk_mul_f32 v[28:29], v[28:29], v[48:49]
	v_mov_b32_e32 v49, v32
	v_mov_b32_e32 v32, v31
	v_lshlrev_b32_e32 v8, 16, v9
	v_and_b32_e32 v9, 0xffff0000, v9
	v_mov_b32_e32 v48, v30
	v_pk_mul_f32 v[30:31], v[32:33], v[14:15]
	v_lshlrev_b32_e32 v22, 16, v23
	v_and_b32_e32 v23, 0xffff0000, v23
	v_pk_fma_f32 v[30:31], v[48:49], v[8:9], v[30:31] neg_lo:[0,0,1] neg_hi:[0,0,1]
	v_pk_mul_f32 v[8:9], v[32:33], v[8:9]
	v_lshlrev_b32_e32 v18, 16, v19
	v_and_b32_e32 v19, 0xffff0000, v19
	v_pk_fma_f32 v[14:15], v[48:49], v[14:15], v[8:9]
	v_pk_mul_f32 v[8:9], v[32:33], v[22:23]
	v_pk_fma_f32 v[28:29], v[56:57], v[52:53], v[28:29]
	v_pk_fma_f32 v[8:9], v[48:49], v[18:19], v[8:9] neg_lo:[0,0,1] neg_hi:[0,0,1]
	v_lshlrev_b32_e32 v42, 16, v10
	v_pk_mul_f32 v[52:53], v[8:9], s[44:45] op_sel_hi:[1,0]
	v_pk_mul_f32 v[8:9], v[32:33], v[18:19]
	v_and_b32_e32 v43, 0xffff0000, v10
	v_pk_fma_f32 v[8:9], v[48:49], v[22:23], v[8:9]
	v_lshlrev_b32_e32 v46, 16, v16
	v_and_b32_e32 v47, 0xffff0000, v16
	v_lshlrev_b32_e32 v50, 16, v20
	v_and_b32_e32 v51, 0xffff0000, v20
	v_lshlrev_b32_e32 v54, 16, v24
	v_and_b32_e32 v55, 0xffff0000, v24
	v_pk_mul_f32 v[18:19], v[8:9], s[44:45] op_sel_hi:[1,0]
	v_mov_b32_e32 v9, v36
	v_mov_b32_e32 v36, v35
	v_mov_b32_e32 v8, v34
	v_pk_mul_f32 v[22:23], v[36:37], v[46:47]
	v_pk_mul_f32 v[32:33], v[36:37], v[42:43]
	v_pk_mul_f32 v[34:35], v[36:37], v[54:55]
	v_pk_mul_f32 v[36:37], v[36:37], v[50:51]
	v_pk_fma_f32 v[22:23], v[8:9], v[42:43], v[22:23] neg_lo:[0,0,1] neg_hi:[0,0,1]
	v_pk_fma_f32 v[32:33], v[8:9], v[46:47], v[32:33]
	v_pk_fma_f32 v[34:35], v[8:9], v[50:51], v[34:35] neg_lo:[0,0,1] neg_hi:[0,0,1]
	v_pk_fma_f32 v[8:9], v[8:9], v[54:55], v[36:37]
	v_lshlrev_b32_e32 v16, 16, v17
	v_and_b32_e32 v17, 0xffff0000, v17
	v_pk_mul_f32 v[36:37], v[8:9], s[44:45] op_sel_hi:[1,0]
	v_mov_b32_e32 v9, v40
	v_mov_b32_e32 v40, v39
	v_lshlrev_b32_e32 v10, 16, v11
	v_and_b32_e32 v11, 0xffff0000, v11
	v_mov_b32_e32 v8, v38
	v_pk_mul_f32 v[38:39], v[40:41], v[16:17]
	v_lshlrev_b32_e32 v24, 16, v25
	v_and_b32_e32 v25, 0xffff0000, v25
	v_pk_fma_f32 v[38:39], v[8:9], v[10:11], v[38:39] neg_lo:[0,0,1] neg_hi:[0,0,1]
	v_pk_mul_f32 v[10:11], v[40:41], v[10:11]
	v_lshlrev_b32_e32 v20, 16, v21
	v_and_b32_e32 v21, 0xffff0000, v21
	v_pk_fma_f32 v[16:17], v[8:9], v[16:17], v[10:11]
	v_pk_mul_f32 v[10:11], v[40:41], v[24:25]
	v_pk_mul_f32 v[44:45], v[44:45], s[44:45] op_sel_hi:[1,0]
	v_pk_fma_f32 v[10:11], v[8:9], v[20:21], v[10:11] neg_lo:[0,0,1] neg_hi:[0,0,1]
	v_pk_mul_f32 v[34:35], v[34:35], s[44:45] op_sel_hi:[1,0]
	v_pk_mul_f32 v[42:43], v[10:11], s[44:45] op_sel_hi:[1,0]
	v_pk_mul_f32 v[10:11], v[40:41], v[20:21]
	v_pk_mul_f32 v[28:29], v[28:29], s[44:45] op_sel_hi:[1,0]
	v_pk_fma_f32 v[8:9], v[8:9], v[24:25], v[10:11]
	v_cvt_pk_bf16_f32 v10, v22, v23
	v_pk_mul_f32 v[20:21], v[8:9], s[44:45] op_sel_hi:[1,0]
	v_cvt_pk_bf16_f32 v8, v26, v27
	v_cvt_pk_bf16_f32 v9, v30, v31
	v_cvt_pk_bf16_f32 v11, v38, v39
	ds_write_b128 v3, v[8:11]
	v_cvt_pk_bf16_f32 v8, v0, v1
	v_cvt_pk_bf16_f32 v9, v14, v15
	v_cvt_pk_bf16_f32 v10, v32, v33
	v_cvt_pk_bf16_f32 v11, v16, v17
	ds_write_b128 v3, v[8:11] offset:128
	v_cvt_pk_bf16_f32 v8, v44, v45
	v_cvt_pk_bf16_f32 v9, v52, v53
	v_cvt_pk_bf16_f32 v10, v34, v35
	v_cvt_pk_bf16_f32 v11, v42, v43
	ds_write_b128 v3, v[8:11] offset:17408
	v_cvt_pk_bf16_f32 v8, v28, v29
	v_cvt_pk_bf16_f32 v9, v18, v19
	v_cvt_pk_bf16_f32 v10, v36, v37
	v_cvt_pk_bf16_f32 v11, v20, v21
	ds_write_b128 v3, v[8:11] offset:17536
	v_bfe_u32 v9, v5, 4, 4
	v_add_u32_e32 v10, v68, v9
	v_and_b32_e32 v8, 0x78, v2
	v_mad_i64_i32 v[0:1], s[0:1], v10, s57, v[66:67]
	v_lshl_add_u64 v[0:1], v[0:1], 0, v[72:73]
	v_lshlrev_b32_e32 v64, 1, v8
	v_lshl_add_u64 v[0:1], v[0:1], 0, v[64:65]
	v_mul_u32_u24_e32 v8, 0x48, v8
	v_lshlrev_b32_e32 v11, 1, v8
	v_lshlrev_b32_e32 v9, 1, v9
	v_add_u32_e32 v14, v4, v11
	v_add3_u32 v13, v4, v9, v11
	v_add_u32_e32 v15, v14, v9
	v_add_u32_e32 v8, 32, v10
	v_mad_i64_i32 v[8:9], s[0:1], v8, s57, v[66:67]
	v_lshl_add_u64 v[8:9], v[8:9], 0, v[72:73]
	v_lshl_add_u64 v[8:9], v[8:9], 0, v[64:65]
	v_and_b32_e32 v20, 15, v5
	v_bfe_u32 v21, v5, 4, 2
	v_lshrrev_b32_e32 v5, 2, v5
	v_and_or_b32 v76, v5, 48, v20
	v_lshlrev_b32_e32 v5, 2, v21
	v_lshlrev_b32_e32 v74, 4, v21
	v_sub_u32_e32 v69, v76, v5
	v_add_u32_e32 v16, -2, v69
	v_cvt_f32_i32_e32 v16, v16
	v_add_u32_e32 v17, -3, v69
	v_subrev_u32_e32 v22, 17, v69
	v_subrev_u32_e32 v23, 18, v69
	v_subrev_u32_e32 v24, 19, v69
	v_subrev_u32_e32 v25, 33, v69
	v_cvt_f32_i32_e32 v17, v17
	v_cvt_f32_i32_e32 v22, v22
	v_cvt_f32_i32_e32 v23, v23
	v_cvt_f32_i32_e32 v24, v24
	v_cvt_f32_i32_e32 v25, v25
	v_subrev_u32_e32 v26, 34, v69
	v_subrev_u32_e32 v27, 35, v69
	v_cvt_f32_i32_e32 v26, v26
	v_cvt_f32_i32_e32 v34, v27
	v_subrev_u32_e32 v28, 49, v69
	s_add_i32 s45, s45, s48
	s_cmpk_gt_i32 s2, 0x62f
	s_waitcnt vmcnt(7) lgkmcnt(0)
	v_mov_b64_e32 v[0:1], v[192:193]
	v_mov_b64_e32 v[2:3], v[194:195]
	ds_write_b16 v13, v0 offset:34816
	ds_write_b16_d16_hi v15, v0 offset:34960
	ds_write_b16 v13, v1 offset:35104
	ds_write_b16_d16_hi v15, v1 offset:35248
	ds_write_b16 v13, v2 offset:35392
	ds_write_b16_d16_hi v15, v2 offset:35536
	ds_write_b16 v13, v3 offset:35680
	ds_write_b16_d16_hi v15, v3 offset:35824
	v_add_u32_e32 v0, v68, v7
	v_mad_i64_i32 v[0:1], s[0:1], v0, s57, v[66:67]
	v_lshl_add_u64 v[0:1], v[0:1], 0, v[72:73]
	v_lshl_add_u64 v[0:1], v[0:1], 0, v[64:65]
	v_lshlrev_b32_e32 v7, 1, v7
	v_add3_u32 v11, v4, v7, v11
	v_add_u32_e32 v7, v14, v7
	s_waitcnt vmcnt(6) lgkmcnt(0)
	v_mov_b64_e32 v[0:1], v[196:197]
	v_mov_b64_e32 v[2:3], v[198:199]
	ds_write_b16 v11, v0 offset:34816
	ds_write_b16_d16_hi v7, v0 offset:34960
	ds_write_b16 v11, v1 offset:35104
	ds_write_b16_d16_hi v7, v1 offset:35248
	ds_write_b16 v11, v2 offset:35392
	ds_write_b16_d16_hi v7, v2 offset:35536
	ds_write_b16 v11, v3 offset:35680
	ds_write_b16_d16_hi v7, v3 offset:35824
	v_cvt_f32_i32_e32 v8, v6
	v_add_u32_e32 v6, 48, v10
	v_mad_i64_i32 v[6:7], s[0:1], v6, s57, v[66:67]
	v_lshl_add_u64 v[6:7], v[6:7], 0, v[72:73]
	v_lshl_add_u64 v[6:7], v[6:7], 0, v[64:65]
	s_waitcnt vmcnt(5) lgkmcnt(0)
	v_mov_b64_e32 v[0:1], v[200:201]
	v_mov_b64_e32 v[2:3], v[202:203]
	ds_write_b16 v13, v0 offset:34880
	ds_write_b16_d16_hi v15, v0 offset:35024
	ds_write_b16 v13, v1 offset:35168
	ds_write_b16_d16_hi v15, v1 offset:35312
	ds_write_b16 v13, v2 offset:35456
	ds_write_b16_d16_hi v15, v2 offset:35600
	ds_write_b16 v13, v3 offset:35744
	ds_write_b16_d16_hi v15, v3 offset:35888
	v_sub_f32_e32 v8, 0xc0a00000, v8
	v_cmp_gt_f32_e32 vcc, s53, v8
	v_add_u32_e32 v9, v4, v74
	v_xad_u32 v10, v5, -1, v76
	v_cndmask_b32_e32 v29, 0, v78, vcc
	v_add_f32_e32 v8, v8, v29
	v_exp_f32_e32 v6, v8
	v_cndmask_b32_e32 v7, 0, v79, vcc
	v_mad_u32_u24 v18, v76, s62, v9
	v_mad_u32_u24 v19, v20, s62, v9
	v_ldexp_f32 v6, v6, v7
	v_sub_f32_e32 v6, 1.0, v6
	v_cmp_gt_f32_e32 vcc, s54, v6
	v_cvt_f32_i32_e32 v9, v69
	v_cvt_f32_i32_e32 v10, v10
	v_cndmask_b32_e64 v7, 0, 32, vcc
	v_ldexp_f32 v6, v6, v7
	v_log_f32_e32 v6, v6
	v_cndmask_b32_e32 v7, 0, v80, vcc
	v_or_b32_e32 v14, 32, v5
	s_waitcnt vmcnt(4) lgkmcnt(0)
	v_mov_b64_e32 v[0:1], v[204:205]
	v_mov_b64_e32 v[2:3], v[206:207]
	ds_write_b16 v13, v0 offset:34912
	ds_write_b16_d16_hi v15, v0 offset:35056
	ds_write_b16 v13, v1 offset:35200
	ds_write_b16_d16_hi v15, v1 offset:35344
	ds_write_b16 v13, v2 offset:35488
	ds_write_b16_d16_hi v15, v2 offset:35632
	ds_write_b16 v13, v3 offset:35776
	ds_write_b16_d16_hi v15, v3 offset:35920
	v_mul_f32_e32 v8, 0x3f317217, v6
	v_fma_f32 v8, v6, s55, -v8
	v_fmac_f32_e32 v8, 0x3377d1cf, v6
	v_fmac_f32_e32 v8, 0x3f317217, v6
	v_cmp_lt_f32_e64 vcc, |v6|, s56
	s_waitcnt lgkmcnt(0)
	s_barrier
	v_add_u32_e32 v254, v68, v76
	v_mul_u32_u24_e32 v254, 0x1a00, v254
	v_lshrrev_b32_e32 v253, 1, v74
	v_add3_u32 v254, v254, v72, v253
	v_add_u32_e32 v254, s46, v254
	global_load_dwordx2 v[252:253], v254, s[38:39]
	global_load_dword v149, v254, s[38:39] offset:128
	v_cndmask_b32_e32 v6, v6, v8, vcc
	v_sub_f32_e32 v6, v6, v7
	ds_read_b128 v[0:3], v19 offset:17408
	v_sub_u32_e32 v14, v76, v14
	v_mul_f32_e32 v83, 0x3fb8aa3b, v6
	v_cvt_f32_i32_e32 v14, v14
	v_mul_f32_e64 v6, |v9|, v83
	v_mul_f32_e64 v7, |v10|, v83
	v_mul_f32_e64 v8, |v16|, v83
	v_cmp_gt_f32_e32 vcc, s53, v6
	v_cmp_gt_f32_e64 s[0:1], s53, v7
	v_cmp_gt_f32_e64 s[4:5], s53, v8
	v_or_b32_e32 v11, 16, v5
	v_or_b32_e32 v5, 48, v5
	v_cndmask_b32_e32 v6, 0, v78, vcc
	v_cndmask_b32_e64 v7, 0, v78, s[0:1]
	v_cndmask_b32_e64 v8, 0, v78, s[4:5]
	v_sub_u32_e32 v11, v76, v11
	v_sub_u32_e32 v5, v76, v5
	v_fma_f32 v42, |v9|, v83, v6
	v_fma_f32 v10, |v10|, v83, v7
	v_fma_f32 v43, |v16|, v83, v8
	ds_read_b128 v[56:59], v18
	ds_read_b128 v[6:9], v19 offset:21760
	v_cvt_f32_i32_e32 v11, v11
	v_cvt_f32_i32_e32 v5, v5
	v_mul_f32_e64 v27, |v17|, v83
	v_mul_f32_e64 v29, |v22|, v83
	v_mul_f32_e64 v30, |v23|, v83
	v_mul_f32_e64 v31, |v24|, v83
	v_mul_f32_e64 v32, |v14|, v83
	v_mul_f32_e64 v33, |v25|, v83
	v_cmp_gt_f32_e64 s[6:7], s53, v27
	v_cmp_gt_f32_e64 s[10:11], s53, v29
	v_cmp_gt_f32_e64 s[12:13], s53, v30
	v_cmp_gt_f32_e64 s[14:15], s53, v31
	v_cmp_gt_f32_e64 s[16:17], s53, v32
	v_cmp_gt_f32_e64 s[18:19], s53, v33
	v_cndmask_b32_e64 v27, 0, v78, s[6:7]
	v_cndmask_b32_e64 v29, 0, v78, s[10:11]
	v_cndmask_b32_e64 v30, 0, v78, s[12:13]
	v_cndmask_b32_e64 v31, 0, v78, s[14:15]
	v_cndmask_b32_e64 v32, 0, v78, s[16:17]
	v_cndmask_b32_e64 v33, 0, v78, s[18:19]
	v_fma_f32 v44, |v17|, v83, v27
	v_fma_f32 v45, |v22|, v83, v29
	v_fma_f32 v48, |v23|, v83, v30
	v_fma_f32 v49, |v24|, v83, v31
	v_fma_f32 v50, |v14|, v83, v32
	v_fma_f32 v13, |v25|, v83, v33
	ds_read_b128 v[60:63], v18 offset:64
	ds_read_b128 v[14:17], v19 offset:17472
	ds_read_b128 v[22:25], v19 offset:26112
	s_waitcnt lgkmcnt(4)
	v_mfma_f32_16x16x32_bf16 v[0:3], v[0:3], v[56:59], 0
	v_cvt_f32_i32_e32 v64, v28
	v_mul_f32_e64 v28, |v11|, v83
	v_mul_f32_e64 v35, |v26|, v83
	v_mul_f32_e64 v36, |v34|, v83
	v_mul_f32_e64 v37, |v5|, v83
	v_cmp_gt_f32_e64 s[8:9], s53, v28
	v_cmp_gt_f32_e64 s[20:21], s53, v35
	v_cmp_gt_f32_e64 s[22:23], s53, v36
	v_cmp_gt_f32_e64 s[24:25], s53, v37
	v_cndmask_b32_e64 v28, 0, v78, s[8:9]
	v_cndmask_b32_e64 v35, 0, v78, s[20:21]
	v_cndmask_b32_e64 v36, 0, v78, s[22:23]
	v_cndmask_b32_e64 v38, 0, v78, s[24:25]
	v_fma_f32 v11, |v11|, v83, v28
	v_fma_f32 v91, |v26|, v83, v35
	ds_read_b128 v[26:29], v19 offset:21824
	ds_read_b128 v[30:33], v19 offset:30464
	v_fma_f32 v93, |v34|, v83, v36
	ds_read_b128 v[34:37], v19 offset:26176
	v_fma_f32 v5, |v5|, v83, v38
	ds_read_b128 v[38:41], v19 offset:30528
	s_waitcnt lgkmcnt(5)
	v_mfma_f32_16x16x32_bf16 v[0:3], v[14:17], v[60:63], v[0:3]
	ds_read_b128 v[14:17], v19 offset:17536
	v_exp_f32_e32 v102, v48
	v_exp_f32_e32 v103, v49
	v_mfma_f32_16x16x32_bf16 v[6:9], v[6:9], v[56:59], 0
	v_exp_f32_e32 v104, v50
	v_exp_f32_e32 v96, v42
	v_exp_f32_e32 v97, v10
	s_waitcnt lgkmcnt(5)
	v_mfma_f32_16x16x32_bf16 v[22:25], v[22:25], v[56:59], 0
	v_exp_f32_e32 v98, v43
	v_exp_f32_e32 v99, v44
	v_exp_f32_e32 v101, v45
	s_waitcnt lgkmcnt(3)
	v_mfma_f32_16x16x32_bf16 v[30:33], v[30:33], v[56:59], 0
	v_mul_f32_e64 v75, |v64|, v83
	v_cndmask_b32_e32 v46, 0, v79, vcc
	v_cndmask_b32_e64 v47, 0, v79, s[0:1]
	v_mfma_f32_16x16x32_bf16 v[6:9], v[26:29], v[60:63], v[6:9]
	ds_read_b128 v[52:55], v18 offset:128
	ds_read_b128 v[26:29], v19 offset:21888
	v_exp_f32_e32 v100, v11
	v_ldexp_f32 v10, v96, v46
	s_waitcnt lgkmcnt(4)
	v_mfma_f32_16x16x32_bf16 v[22:25], v[34:37], v[60:63], v[22:25]
	v_ldexp_f32 v11, v97, v47
	v_cmp_gt_f32_e32 vcc, s53, v75
	v_cndmask_b32_e64 v77, 0, v79, s[4:5]
	s_waitcnt lgkmcnt(3)
	v_mfma_f32_16x16x32_bf16 v[30:33], v[38:41], v[60:63], v[30:33]
	ds_read_b128 v[48:51], v18 offset:192
	ds_read_b128 v[34:37], v19 offset:17600
	ds_read_b128 v[38:41], v19 offset:26240
	v_cndmask_b32_e64 v84, 0, v79, s[6:7]
	v_ldexp_f32 v18, v98, v77
	s_waitcnt lgkmcnt(4)
	v_mfma_f32_16x16x32_bf16 v[0:3], v[14:17], v[52:55], v[0:3]
	ds_read_b128 v[14:17], v19 offset:21952
	ds_read_b128 v[42:45], v19 offset:30592
	v_exp_f32_e32 v13, v13
	v_exp_f32_e32 v91, v91
	s_waitcnt lgkmcnt(3)
	v_mfma_f32_16x16x32_bf16 v[0:3], v[34:37], v[48:51], v[0:3]
	v_exp_f32_e32 v93, v93
	v_cndmask_b32_e64 v90, 0, v79, s[18:19]
	v_cndmask_b32_e64 v89, 0, v79, s[16:17]
	v_mfma_f32_16x16x32_bf16 v[6:9], v[26:29], v[52:55], v[6:9]
	ds_read_b128 v[26:29], v19 offset:26304
	s_nop 2
	v_pk_mul_f32 v[10:11], v[10:11], v[0:1]
	v_cndmask_b32_e32 v0, 0, v78, vcc
	v_fma_f32 v0, |v64|, v83, v0
	v_subrev_u32_e32 v1, 50, v69
	s_waitcnt lgkmcnt(3)
	v_mfma_f32_16x16x32_bf16 v[22:25], v[38:41], v[52:55], v[22:25]
	v_exp_f32_e32 v0, v0
	v_cvt_f32_i32_e32 v1, v1
	ds_read_b128 v[38:41], v19 offset:30656
	v_ldexp_f32 v19, v99, v84
	v_pk_mul_f32 v[18:19], v[18:19], v[2:3]
	v_cndmask_b32_e32 v2, 0, v79, vcc
	s_waitcnt lgkmcnt(3)
	v_mfma_f32_16x16x32_bf16 v[6:9], v[14:17], v[48:51], v[6:9]
	v_lshlrev_b32_e32 v64, 3, v21
	v_cndmask_b32_e64 v92, 0, v79, s[20:21]
	v_cndmask_b32_e64 v94, 0, v79, s[22:23]
	s_waitcnt lgkmcnt(1)
	v_mfma_f32_16x16x32_bf16 v[14:17], v[26:29], v[48:51], v[22:25]
	v_ldexp_f32 v29, v0, v2
	v_mul_f32_e64 v0, |v1|, v83
	v_cmp_gt_f32_e32 vcc, s53, v0
	v_mfma_f32_16x16x32_bf16 v[30:33], v[42:45], v[52:55], v[30:33]
	v_ldexp_f32 v43, v13, v90
	v_cndmask_b32_e32 v0, 0, v78, vcc
	v_fma_f32 v13, |v1|, v83, v0
	v_mul_u32_u24_e32 v0, 0x90, v20
	v_add3_u32 v21, v4, v64, v0
	v_exp_f32_e32 v5, v5
	v_ldexp_f32 v42, v104, v89
	v_ldexp_f32 v26, v91, v92
	v_ldexp_f32 v27, v93, v94
	v_add_u32_e32 v92, 0x9800, v21
	v_pk_mul_f32 v[46:47], v[42:43], v[14:15]
	v_pk_mul_f32 v[90:91], v[26:27], v[16:17]
	ds_read2_b64 v[14:17], v92 offset0:64 offset1:68
	v_exp_f32_e32 v13, v13
	v_cndmask_b32_e64 v95, 0, v79, s[24:25]
	v_ldexp_f32 v28, v5, v95
	v_cvt_pk_bf16_f32 v5, v18, v19
	v_cndmask_b32_e32 v18, 0, v79, vcc
	v_ldexp_f32 v18, v13, v18
	v_subrev_u32_e32 v13, 51, v69
	v_cndmask_b32_e64 v85, 0, v79, s[8:9]
	v_cndmask_b32_e64 v86, 0, v79, s[10:11]
	v_cndmask_b32_e64 v87, 0, v79, s[12:13]
	v_cndmask_b32_e64 v88, 0, v79, s[14:15]
	s_waitcnt lgkmcnt(1)
	v_mfma_f32_16x16x32_bf16 v[22:25], v[38:41], v[48:51], v[30:33]
	v_cvt_f32_i32_e32 v13, v13
	v_ldexp_f32 v34, v100, v85
	v_ldexp_f32 v35, v101, v86
	v_ldexp_f32 v36, v102, v87
	v_ldexp_f32 v37, v103, v88
	v_pk_mul_f32 v[6:7], v[34:35], v[6:7]
	v_pk_mul_f32 v[30:31], v[36:37], v[8:9]
	v_add_u32_e32 v75, 0x8800, v21
	v_cvt_pk_bf16_f32 v4, v10, v11
	v_add_u32_e32 v77, 0x9000, v21
	v_cvt_pk_bf16_f32 v6, v6, v7
	v_cvt_pk_bf16_f32 v7, v30, v31
	v_add_u32_e32 v93, 0xa000, v21
	v_add_u32_e32 v94, 0xa800, v21
	v_add_u32_e32 v69, 0xb000, v21
	v_add_u32_e32 v95, 0xb800, v21
	v_add_u32_e32 v96, 0xc000, v21
	v_pk_mul_f32 v[22:23], v[28:29], v[22:23]
	ds_read2_b64 v[0:3], v75 offset1:4
	ds_read2_b64 v[8:11], v77 offset0:32 offset1:36
	ds_read2_b64 v[26:29], v93 offset0:96 offset1:100
	ds_read2_b64 v[30:33], v94 offset0:128 offset1:132
	s_waitcnt lgkmcnt(4)
	v_mfma_f32_16x16x32_bf16 v[34:37], v[14:17], v[4:7], 0
	ds_read2_b64 v[14:17], v69 offset0:160 offset1:164
	v_mul_f32_e64 v19, |v13|, v83
	ds_read2_b64 v[38:41], v95 offset0:192 offset1:196
	ds_read2_b64 v[42:45], v96 offset0:224 offset1:228
	v_cmp_gt_f32_e32 vcc, s53, v19
	s_waitcnt lgkmcnt(6)
	v_mfma_f32_16x16x32_bf16 v[0:3], v[0:3], v[4:7], 0
	v_cvt_pk_bf16_f32 v89, v90, v91
	v_cndmask_b32_e32 v19, 0, v78, vcc
	v_fma_f32 v13, |v13|, v83, v19
	v_exp_f32_e32 v13, v13
	v_cndmask_b32_e32 v19, 0, v79, vcc
	s_waitcnt lgkmcnt(5)
	v_mfma_f32_16x16x32_bf16 v[8:11], v[8:11], v[4:7], 0
	v_cvt_pk_bf16_f32 v90, v22, v23
	v_ldexp_f32 v19, v13, v19
	v_pk_mul_f32 v[18:19], v[18:19], v[24:25]
	s_waitcnt lgkmcnt(4)
	v_mfma_f32_16x16x32_bf16 v[26:29], v[26:29], v[4:7], 0
	ds_read2_b64 v[22:25], v92 offset0:72 offset1:76
	v_cvt_pk_bf16_f32 v88, v46, v47
	v_cvt_pk_bf16_f32 v91, v18, v19
	s_waitcnt lgkmcnt(4)
	v_mfma_f32_16x16x32_bf16 v[30:33], v[30:33], v[4:7], 0
	v_ashrrev_i32_e32 v13, 31, v12
	v_lshlrev_b64 v[12:13], 15, v[12:13]
	v_lshlrev_b32_e32 v20, 8, v20
	s_waitcnt lgkmcnt(3)
	v_mfma_f32_16x16x32_bf16 v[84:87], v[14:17], v[4:7], 0
	ds_read2_b64 v[14:17], v75 offset0:8 offset1:12
	v_mov_b32_e32 v75, v65
	v_mov_b32_e32 v21, v65
	s_waitcnt lgkmcnt(3)
	v_mfma_f32_16x16x32_bf16 v[38:41], v[38:41], v[4:7], 0
	v_readlane_b32 s4, v255, 2
	v_readlane_b32 s6, v255, 4
	v_readlane_b32 s7, v255, 5
	s_waitcnt lgkmcnt(2)
	v_mfma_f32_16x16x32_bf16 v[42:45], v[42:45], v[4:7], 0
	ds_read2_b64 v[4:7], v77 offset0:40 offset1:44
	v_mov_b32_e32 v77, v65
	v_readlane_b32 s5, v255, 3
	s_waitcnt lgkmcnt(1)
	v_mfma_f32_16x16x32_bf16 v[16:19], v[14:17], v[88:91], v[0:3]
	v_readlane_b32 s8, v255, 6
	v_readlane_b32 s9, v255, 7
	v_readlane_b32 s10, v255, 8
	s_waitcnt lgkmcnt(0)
	v_mfma_f32_16x16x32_bf16 v[0:3], v[4:7], v[88:91], v[8:11]
	v_readlane_b32 s11, v255, 9
	s_nop 1
	ds_read2_b64 v[8:11], v93 offset0:104 offset1:108
	v_readlane_b32 s12, v255, 10
	v_mfma_f32_16x16x32_bf16 v[4:7], v[22:25], v[88:91], v[34:37]
	ds_read2_b64 v[22:25], v94 offset0:136 offset1:140
	v_readlane_b32 s13, v255, 11
	v_readlane_b32 s14, v255, 12
	s_waitcnt lgkmcnt(1)
	v_mfma_f32_16x16x32_bf16 v[8:11], v[8:11], v[88:91], v[26:29]
	s_nop 2
	v_lshl_add_u64 v[26:27], s[42:43], 0, v[12:13]
	v_lshl_add_u64 v[26:27], v[26:27], 0, v[74:75]
	v_lshl_add_u64 v[108:109], v[26:27], 0, v[20:21]
	s_waitcnt lgkmcnt(0)
	v_mfma_f32_16x16x32_bf16 v[12:15], v[22:25], v[88:91], v[30:33]
	ds_read2_b64 v[22:25], v69 offset0:168 offset1:172
	v_add_co_u32_e32 v134, vcc, s63, v108
	s_nop 1
	v_addc_co_u32_e32 v135, vcc, 0, v109, vcc
	v_add_co_u32_e32 v136, vcc, s64, v108
	s_nop 1
	v_addc_co_u32_e32 v137, vcc, 0, v109, vcc
	v_add_co_u32_e32 v138, vcc, s65, v108
	s_nop 1
	v_addc_co_u32_e32 v139, vcc, 0, v109, vcc
	v_add_co_u32_e32 v140, vcc, s66, v108
	s_nop 1
	v_addc_co_u32_e32 v141, vcc, 0, v109, vcc
	v_add_co_u32_e32 v142, vcc, s67, v108
	s_nop 1
	v_addc_co_u32_e32 v143, vcc, 0, v109, vcc
	v_add_co_u32_e32 v150, vcc, s68, v108
	s_nop 1
	v_addc_co_u32_e32 v151, vcc, 0, v109, vcc
	v_add_co_u32_e32 v152, vcc, s69, v108
	s_nop 1
	v_addc_co_u32_e32 v153, vcc, 0, v109, vcc
	global_load_dwordx4 v[160:163], v[108:109], off
	global_load_dwordx4 v[164:167], v[108:109], off offset:64
	global_load_dwordx4 v[168:171], v[108:109], off offset:128
	global_load_dwordx4 v[172:175], v[108:109], off offset:192
	global_load_dwordx4 v[176:179], v[134:135], off
	global_load_dwordx4 v[180:183], v[134:135], off offset:64
	global_load_dwordx4 v[184:187], v[134:135], off offset:128
	global_load_dwordx4 v[188:191], v[134:135], off offset:192
	global_load_dwordx4 v[192:195], v[136:137], off
	global_load_dwordx4 v[196:199], v[136:137], off offset:64
	global_load_dwordx4 v[200:203], v[136:137], off offset:128
	global_load_dwordx4 v[204:207], v[136:137], off offset:192
	global_load_dwordx4 v[208:211], v[138:139], off
	global_load_dwordx4 v[212:215], v[138:139], off offset:64
	global_load_dwordx4 v[216:219], v[138:139], off offset:128
	global_load_dwordx4 v[220:223], v[138:139], off offset:192
	global_load_dwordx4 v[224:227], v[140:141], off
	global_load_dwordx4 v[228:231], v[140:141], off offset:64
	global_load_dwordx4 v[232:235], v[140:141], off offset:128
	global_load_dwordx4 v[236:239], v[140:141], off offset:192
	global_load_dwordx4 v[240:243], v[142:143], off
	global_load_dwordx4 v[244:247], v[142:143], off offset:64
	global_load_dwordx4 v[248:251], v[142:143], off offset:128
	ds_read2_b64 v[30:33], v95 offset0:200 offset1:204
	s_waitcnt lgkmcnt(0)
	v_mfma_f32_16x16x32_bf16 v[20:23], v[22:25], v[88:91], v[84:87]
	v_ashrrev_i32_e32 v69, 31, v68
	v_mfma_f32_16x16x32_bf16 v[84:87], v[30:33], v[88:91], v[38:41]
	ds_read2_b64 v[30:33], v96 offset0:232 offset1:236
	s_waitcnt lgkmcnt(0)
	v_mfma_f32_16x16x32_bf16 v[88:91], v[30:33], v[88:91], v[42:45]
	s_nop 0
	s_waitcnt lgkmcnt(0)
	global_load_dwordx4 v[96:99], v[142:143], off offset:192
	global_load_dwordx4 v[100:103], v[150:151], off
	global_load_dwordx4 v[104:107], v[150:151], off offset:64
	s_waitcnt vmcnt(22)
	v_mfma_f32_16x16x32_bf16 v[36:39], v[160:163], v[56:59], 0
	v_mfma_f32_16x16x32_bf16 v[36:39], v[164:167], v[60:63], v[36:39]
	v_mfma_f32_16x16x32_bf16 v[36:39], v[168:171], v[52:55], v[36:39]
	v_mfma_f32_16x16x32_bf16 v[36:39], v[172:175], v[48:51], v[36:39]
	global_load_dwordx4 v[160:163], v[150:151], off offset:128
	global_load_dwordx4 v[164:167], v[150:151], off offset:192
	global_load_dwordx4 v[168:171], v[152:153], off
	global_load_dwordx4 v[172:175], v[152:153], off offset:64
	s_waitcnt vmcnt(22)
	v_mfma_f32_16x16x32_bf16 v[24:27], v[176:179], v[56:59], 0
	v_mfma_f32_16x16x32_bf16 v[24:27], v[180:183], v[60:63], v[24:27]
	v_mfma_f32_16x16x32_bf16 v[24:27], v[184:187], v[52:55], v[24:27]
	v_mfma_f32_16x16x32_bf16 v[24:27], v[188:191], v[48:51], v[24:27]
	global_load_dwordx4 v[176:179], v[152:153], off offset:128
	global_load_dwordx4 v[180:183], v[152:153], off offset:192
	s_waitcnt vmcnt(20)
	v_mfma_f32_16x16x32_bf16 v[28:31], v[192:195], v[56:59], 0
	v_mfma_f32_16x16x32_bf16 v[28:31], v[196:199], v[60:63], v[28:31]
	v_mfma_f32_16x16x32_bf16 v[28:31], v[200:203], v[52:55], v[28:31]
	v_mfma_f32_16x16x32_bf16 v[28:31], v[204:207], v[48:51], v[28:31]
	s_waitcnt vmcnt(16)
	v_mfma_f32_16x16x32_bf16 v[32:35], v[208:211], v[56:59], 0
	v_mfma_f32_16x16x32_bf16 v[32:35], v[212:215], v[60:63], v[32:35]
	v_mfma_f32_16x16x32_bf16 v[32:35], v[216:219], v[52:55], v[32:35]
	v_mfma_f32_16x16x32_bf16 v[32:35], v[220:223], v[48:51], v[32:35]
	s_waitcnt vmcnt(12)
	v_mfma_f32_16x16x32_bf16 v[40:43], v[224:227], v[56:59], 0
	v_mfma_f32_16x16x32_bf16 v[40:43], v[228:231], v[60:63], v[40:43]
	v_mfma_f32_16x16x32_bf16 v[40:43], v[232:235], v[52:55], v[40:43]
	v_mfma_f32_16x16x32_bf16 v[40:43], v[236:239], v[48:51], v[40:43]
	s_waitcnt vmcnt(8)
	v_mfma_f32_16x16x32_bf16 v[44:47], v[240:243], v[56:59], 0
	v_mfma_f32_16x16x32_bf16 v[44:47], v[244:247], v[60:63], v[44:47]
	v_mfma_f32_16x16x32_bf16 v[44:47], v[248:251], v[52:55], v[44:47]
	v_mfma_f32_16x16x32_bf16 v[44:47], v[96:99], v[48:51], v[44:47]
	s_waitcnt vmcnt(4)
	v_mfma_f32_16x16x32_bf16 v[92:95], v[100:103], v[56:59], 0
	v_mfma_f32_16x16x32_bf16 v[92:95], v[104:107], v[60:63], v[92:95]
	v_mfma_f32_16x16x32_bf16 v[92:95], v[160:163], v[52:55], v[92:95]
	v_mfma_f32_16x16x32_bf16 v[92:95], v[164:167], v[48:51], v[92:95]
	s_waitcnt vmcnt(0)
	v_mfma_f32_16x16x32_bf16 v[56:59], v[168:171], v[56:59], 0
	v_mfma_f32_16x16x32_bf16 v[56:59], v[172:175], v[60:63], v[56:59]
	v_mfma_f32_16x16x32_bf16 v[52:55], v[176:179], v[52:55], v[56:59]
	v_mfma_f32_16x16x32_bf16 v[48:51], v[180:183], v[48:51], v[52:55]
	v_readlane_b32 s15, v255, 13
	v_readlane_b32 s16, v255, 14
	v_readlane_b32 s17, v255, 15
	v_readlane_b32 s18, v255, 16
	v_readlane_b32 s19, v255, 17
	s_waitcnt lgkmcnt(0)
	s_nop 5
	s_waitcnt lgkmcnt(0)
	s_nop 2
	s_nop 2
	s_waitcnt lgkmcnt(0)
	s_nop 0
	s_nop 3
	s_waitcnt lgkmcnt(0)
	s_waitcnt lgkmcnt(0)
	s_waitcnt lgkmcnt(0)
	s_nop 0
	s_waitcnt lgkmcnt(0)
	s_nop 0
	s_waitcnt lgkmcnt(0)
	s_waitcnt lgkmcnt(0)
	s_nop 0
	s_waitcnt lgkmcnt(0)
	v_lshl_add_u64 v[100:101], v[68:69], 0, v[76:77]
	v_mad_u64_u32 v[60:61], s[0:1], v100, s57, v[66:67]
	v_mad_i32_i24 v61, v101, s57, v61
	v_lshl_add_u64 v[60:61], v[60:61], 0, v[72:73]
	v_lshl_add_u64 v[102:103], v[60:61], 0, v[64:65]
	v_add_co_u32_e32 v60, vcc, s63, v102
	s_waitcnt lgkmcnt(0)
	v_addc_co_u32_e32 v61, vcc, 0, v103, vcc
	v_mov_b64_e32 v[68:69], v[252:253]
	v_lshl_add_u64 v[232:233], v[102:103], 0, s[46:47]
	v_lshl_add_u64 v[234:235], v[70:71], 2, s[6:7]
	v_lshl_add_u64 v[234:235], v[234:235], 0, v[74:75]
	global_load_dwordx2 v[186:187], v[232:233], off offset:32
	global_load_dwordx2 v[188:189], v[232:233], off offset:64
	global_load_dwordx2 v[190:191], v[232:233], off offset:96
	global_load_dwordx2 v[192:193], v[232:233], off offset:128
	global_load_dwordx2 v[194:195], v[232:233], off offset:160
	global_load_dwordx2 v[196:197], v[232:233], off offset:192
	global_load_dwordx2 v[198:199], v[232:233], off offset:224
	global_load_dwordx4 v[204:207], v[234:235], off offset:64
	global_load_dwordx4 v[208:211], v[234:235], off offset:128
	global_load_dwordx4 v[212:215], v[234:235], off offset:192
	global_load_dwordx4 v[216:219], v[234:235], off offset:256
	global_load_dwordx4 v[220:223], v[234:235], off offset:320
	global_load_dwordx4 v[224:227], v[234:235], off offset:384
	global_load_dwordx4 v[228:231], v[234:235], off offset:448
	s_nop 0
	v_add_u32_e32 v56, 1, v76
	v_cvt_f32_ubyte0_e32 v56, v56
	v_mul_f32_e32 v57, v83, v56
	v_cmp_gt_f32_e32 vcc, s53, v57
	s_waitcnt vmcnt(0) lgkmcnt(0)
	v_lshlrev_b32_e32 v77, 16, v68
	v_cndmask_b32_e32 v57, 0, v78, vcc
	v_fmac_f32_e32 v57, v83, v56
	v_exp_f32_e32 v56, v57
	v_cndmask_b32_e32 v52, 0, v79, vcc
	v_and_b32_e32 v68, 0xffff0000, v68
	v_cmp_lt_i32_e32 vcc, v157, v156
	v_ldexp_f32 v62, v56, v52
	v_pk_fma_f32 v[58:59], v[62:63], v[50:51], v[90:91] op_sel_hi:[0,1,1]
	v_lshlrev_b64 v[50:51], 11, v[100:101]
	v_lshl_add_u64 v[50:51], s[30:31], 0, v[50:51]
	v_lshl_add_u64 v[52:53], v[50:51], 0, v[72:73]
	v_mul_f32_e32 v72, 0xbfb8aa3b, v77
	v_pk_fma_f32 v[54:55], v[62:63], v[92:93], v[84:85] op_sel_hi:[0,1,1]
	v_exp_f32_e32 v84, v72
	v_mul_f32_e32 v72, 0xbfb8aa3b, v68
	v_exp_f32_e32 v85, v72
	v_pk_fma_f32 v[60:61], v[62:63], v[48:49], v[88:89] op_sel_hi:[0,1,1]
	v_cndmask_b32_e32 v48, v155, v157, vcc
	v_cmp_lt_i32_e32 vcc, v158, v156
	v_lshlrev_b32_e32 v76, 2, v48
	v_pk_fma_f32 v[56:57], v[62:63], v[94:95], v[86:87] op_sel_hi:[0,1,1]
	v_cndmask_b32_e32 v48, v155, v158, vcc
	v_lshlrev_b32_e32 v63, 2, v48
	v_pk_fma_f32 v[18:19], v[62:63], v[38:39], v[18:19] op_sel_hi:[0,1,1]
	v_pk_add_f32 v[38:39], v[84:85], 1.0 op_sel_hi:[1,0]
	v_lshlrev_b32_e32 v83, 16, v69
	v_and_b32_e32 v86, 0xffff0000, v69
	v_div_scale_f32 v69, s[0:1], v39, v39, v68
	v_rcp_f32_e32 v84, v69
	v_pk_fma_f32 v[16:17], v[62:63], v[36:37], v[16:17] op_sel_hi:[0,1,1]
	v_add_f32_e32 v36, 0, v16
	v_add_f32_e32 v85, v17, v36
	v_fma_f32 v36, -v69, v84, 1.0
	v_fmac_f32_e32 v84, v36, v84
	v_div_scale_f32 v36, vcc, v68, v39, v68
	v_mul_f32_e32 v37, v36, v84
	v_fma_f32 v87, -v69, v37, v36
	v_fmac_f32_e32 v37, v87, v84
	v_div_scale_f32 v87, s[0:1], v38, v38, v77
	v_rcp_f32_e32 v88, v87
	v_fma_f32 v36, -v69, v37, v36
	v_div_fmas_f32 v36, v36, v84, v37
	v_div_fixup_f32 v37, v36, v39, v68
	v_fma_f32 v36, -v87, v88, 1.0
	v_fmac_f32_e32 v88, v36, v88
	v_div_scale_f32 v36, vcc, v77, v38, v77
	v_mul_f32_e32 v39, v36, v88
	v_fma_f32 v68, -v87, v39, v36
	v_fmac_f32_e32 v39, v68, v88
	v_fma_f32 v36, -v87, v39, v36
	v_div_fmas_f32 v36, v36, v88, v39
	v_div_fixup_f32 v36, v36, v38, v77
	v_add_f32_e32 v38, v18, v85
	v_add_f32_e32 v38, v19, v38
	v_pk_fma_f32 v[0:1], v[62:63], v[24:25], v[0:1] op_sel_hi:[0,1,1]
	v_add_f32_e32 v24, v38, v0
	v_pk_fma_f32 v[2:3], v[62:63], v[26:27], v[2:3] op_sel_hi:[0,1,1]
	v_add_f32_e32 v24, v1, v24
	v_add_f32_e32 v24, v2, v24
	v_add_f32_e32 v24, v3, v24
	v_pk_fma_f32 v[4:5], v[62:63], v[28:29], v[4:5] op_sel_hi:[0,1,1]
	v_add_f32_e32 v24, v24, v4
	v_pk_fma_f32 v[6:7], v[62:63], v[30:31], v[6:7] op_sel_hi:[0,1,1]
	v_add_f32_e32 v24, v5, v24
	v_add_f32_e32 v24, v6, v24
	v_add_f32_e32 v24, v7, v24
	v_pk_fma_f32 v[8:9], v[62:63], v[32:33], v[8:9] op_sel_hi:[0,1,1]
	v_add_f32_e32 v24, v24, v8
	v_pk_fma_f32 v[10:11], v[62:63], v[34:35], v[10:11] op_sel_hi:[0,1,1]
	v_add_f32_e32 v24, v9, v24
	v_add_f32_e32 v24, v10, v24
	v_add_f32_e32 v24, v11, v24
	v_pk_fma_f32 v[12:13], v[62:63], v[40:41], v[12:13] op_sel_hi:[0,1,1]
	v_add_f32_e32 v24, v24, v12
	v_pk_fma_f32 v[14:15], v[62:63], v[42:43], v[14:15] op_sel_hi:[0,1,1]
	v_add_f32_e32 v24, v13, v24
	v_lshl_add_u64 v[48:49], v[70:71], 2, s[6:7]
	v_add_f32_e32 v24, v14, v24
	v_lshl_add_u64 v[48:49], v[48:49], 0, v[74:75]
	v_add_f32_e32 v28, v15, v24
	v_pk_fma_f32 v[26:27], v[62:63], v[44:45], v[20:21] op_sel_hi:[0,1,1]
	global_load_dwordx4 v[72:75], v[48:49], off
	v_add_f32_e32 v20, v28, v26
	v_pk_fma_f32 v[24:25], v[62:63], v[46:47], v[22:23] op_sel_hi:[0,1,1]
	v_add_f32_e32 v20, v27, v20
	v_add_f32_e32 v20, v24, v20
	v_add_f32_e32 v20, v25, v20
	v_add_f32_e32 v20, v20, v54
	v_add_f32_e32 v20, v55, v20
	v_mul_f32_e32 v68, 0xbfb8aa3b, v83
	v_mul_f32_e32 v69, 0xbfb8aa3b, v86
	v_add_f32_e32 v20, v56, v20
	v_exp_f32_e32 v68, v68
	v_exp_f32_e32 v69, v69
	v_add_f32_e32 v20, v57, v20
	v_add_f32_e32 v20, v20, v60
	v_add_f32_e32 v20, v61, v20
	v_add_f32_e32 v20, v58, v20
	v_pk_add_f32 v[68:69], v[68:69], 1.0 op_sel_hi:[1,0]
	v_add_f32_e32 v20, v59, v20
	v_div_scale_f32 v39, s[0:1], v69, v69, v86
	ds_bpermute_b32 v21, v76, v20
	v_rcp_f32_e32 v84, v39
	v_lshl_add_u64 v[50:51], v[102:103], 0, s[46:47]
	v_fma_f32 v77, -v39, v84, 1.0
	s_waitcnt lgkmcnt(0)
	v_add_f32_e32 v20, v20, v21
	v_fmac_f32_e32 v84, v77, v84
	v_div_scale_f32 v77, vcc, v86, v69, v86
	ds_bpermute_b32 v21, v63, v20
	v_mul_f32_e32 v85, v77, v84
	v_fma_f32 v87, -v39, v85, v77
	v_fmac_f32_e32 v85, v87, v84
	v_fma_f32 v22, -v39, v85, v77
	v_div_fmas_f32 v22, v22, v84, v85
	s_waitcnt lgkmcnt(0)
	v_add_f32_e32 v20, v20, v21
	v_div_fixup_f32 v29, v22, v69, v86
	v_mul_f32_e32 v28, 0x3c000000, v20
	v_pk_add_f32 v[32:33], v[16:17], v[28:29] op_sel_hi:[1,0] neg_lo:[0,1] neg_hi:[0,1]
	v_pk_add_f32 v[38:39], v[18:19], v[28:29] op_sel_hi:[1,0] neg_lo:[0,1] neg_hi:[0,1]
	v_pk_mul_f32 v[34:35], v[32:33], v[32:33]
	v_pk_mul_f32 v[40:41], v[38:39], v[38:39]
	v_pk_add_f32 v[42:43], v[0:1], v[28:29] op_sel_hi:[1,0] neg_lo:[0,1] neg_hi:[0,1]
	v_pk_add_f32 v[46:47], v[2:3], v[28:29] op_sel_hi:[1,0] neg_lo:[0,1] neg_hi:[0,1]
	v_pk_add_f32 v[84:85], v[4:5], v[28:29] op_sel_hi:[1,0] neg_lo:[0,1] neg_hi:[0,1]
	v_pk_add_f32 v[88:89], v[6:7], v[28:29] op_sel_hi:[1,0] neg_lo:[0,1] neg_hi:[0,1]
	v_pk_add_f32 v[22:23], v[8:9], v[28:29] op_sel_hi:[1,0] neg_lo:[0,1] neg_hi:[0,1]
	v_pk_add_f32 v[20:21], v[10:11], v[28:29] op_sel_hi:[1,0] neg_lo:[0,1] neg_hi:[0,1]
	v_pk_add_f32 v[18:19], v[12:13], v[28:29] op_sel_hi:[1,0] neg_lo:[0,1] neg_hi:[0,1]
	v_pk_add_f32 v[16:17], v[14:15], v[28:29] op_sel_hi:[1,0] neg_lo:[0,1] neg_hi:[0,1]
	v_pk_add_f32 v[14:15], v[26:27], v[28:29] op_sel_hi:[1,0] neg_lo:[0,1] neg_hi:[0,1]
	v_pk_add_f32 v[12:13], v[24:25], v[28:29] op_sel_hi:[1,0] neg_lo:[0,1] neg_hi:[0,1]
	v_pk_add_f32 v[4:5], v[60:61], v[28:29] op_sel_hi:[1,0] neg_lo:[0,1] neg_hi:[0,1]
	v_pk_add_f32 v[0:1], v[58:59], v[28:29] op_sel_hi:[1,0] neg_lo:[0,1] neg_hi:[0,1]
	v_pk_add_f32 v[8:9], v[56:57], v[28:29] op_sel_hi:[1,0] neg_lo:[0,1] neg_hi:[0,1]
	v_pk_add_f32 v[10:11], v[54:55], v[28:29] op_sel_hi:[1,0] neg_lo:[0,1] neg_hi:[0,1]
	v_add_f32_e32 v28, v34, v35
	v_add_f32_e32 v28, v40, v28
	v_pk_mul_f32 v[44:45], v[42:43], v[42:43]
	v_add_f32_e32 v28, v41, v28
	v_add_f32_e32 v28, v44, v28
	v_pk_mul_f32 v[2:3], v[46:47], v[46:47]
	v_add_f32_e32 v28, v45, v28
	v_add_f32_e32 v2, v2, v28
	v_pk_mul_f32 v[86:87], v[84:85], v[84:85]
	v_add_f32_e32 v2, v3, v2
	v_add_f32_e32 v2, v86, v2
	v_pk_mul_f32 v[6:7], v[88:89], v[88:89]
	v_add_f32_e32 v2, v87, v2
	v_add_f32_e32 v2, v6, v2
	v_pk_mul_f32 v[90:91], v[22:23], v[22:23]
	v_add_f32_e32 v2, v7, v2
	v_add_f32_e32 v2, v90, v2
	v_pk_mul_f32 v[92:93], v[20:21], v[20:21]
	v_add_f32_e32 v2, v91, v2
	v_add_f32_e32 v2, v92, v2
	v_pk_mul_f32 v[94:95], v[18:19], v[18:19]
	v_add_f32_e32 v2, v93, v2
	v_add_f32_e32 v2, v94, v2
	v_pk_mul_f32 v[96:97], v[16:17], v[16:17]
	v_add_f32_e32 v2, v95, v2
	v_add_f32_e32 v2, v96, v2
	v_pk_mul_f32 v[26:27], v[14:15], v[14:15]
	v_add_f32_e32 v2, v97, v2
	v_add_f32_e32 v2, v26, v2
	v_pk_mul_f32 v[24:25], v[12:13], v[12:13]
	v_add_f32_e32 v2, v27, v2
	v_add_f32_e32 v2, v24, v2
	v_pk_mul_f32 v[54:55], v[10:11], v[10:11]
	v_add_f32_e32 v2, v25, v2
	v_add_f32_e32 v2, v54, v2
	v_pk_mul_f32 v[56:57], v[8:9], v[8:9]
	v_add_f32_e32 v2, v55, v2
	v_add_f32_e32 v2, v56, v2
	v_pk_mul_f32 v[60:61], v[4:5], v[4:5]
	v_add_f32_e32 v2, v57, v2
	v_add_f32_e32 v2, v60, v2
	v_pk_mul_f32 v[58:59], v[0:1], v[0:1]
	v_add_f32_e32 v2, v61, v2
	v_add_f32_e32 v2, v58, v2
	v_add_f32_e32 v2, v59, v2
	ds_bpermute_b32 v3, v76, v2
	v_div_scale_f32 v62, s[0:1], v68, v68, v83
	v_rcp_f32_e32 v69, v62
	s_waitcnt vmcnt(0)
	v_lshlrev_b32_e32 v40, 16, v31
	s_waitcnt lgkmcnt(0)
	v_add_f32_e32 v2, v2, v3
	ds_bpermute_b32 v3, v63, v2
	v_fma_f32 v6, -v62, v69, 1.0
	v_fmac_f32_e32 v69, v6, v69
	v_div_scale_f32 v6, vcc, v83, v68, v83
	s_waitcnt lgkmcnt(0)
	v_add_f32_e32 v2, v2, v3
	v_fmamk_f32 v2, v2, 0x3c000000, v81
	v_mul_f32_e32 v7, v6, v69
	v_mul_f32_e32 v3, 0x4b800000, v2
	v_cmp_gt_f32_e64 s[0:1], s54, v2
	v_fma_f32 v24, -v62, v7, v6
	v_fmac_f32_e32 v7, v24, v69
	v_cndmask_b32_e64 v2, v2, v3, s[0:1]
	v_rsq_f32_e32 v24, v2
	v_fma_f32 v6, -v62, v7, v6
	v_div_fmas_f32 v2, v6, v69, v7
	v_div_fixup_f32 v28, v2, v68, v83
	v_mul_f32_e32 v6, 0x45800000, v24
	v_cndmask_b32_e64 v6, v24, v6, s[0:1]
	v_pk_mul_f32 v[24:25], v[32:33], v[6:7] op_sel_hi:[1,0]
	v_pk_mul_f32 v[26:27], v[38:39], v[6:7] op_sel_hi:[1,0]
	v_pk_mul_f32 v[24:25], v[72:73], v[24:25]
	v_pk_mul_f32 v[26:27], v[74:75], v[26:27]
	v_pk_mul_f32 v[24:25], v[36:37], v[24:25]
	v_pk_mul_f32 v[26:27], v[28:29], v[26:27]
	v_lshl_add_u64 v[2:3], v[52:53], 0, v[64:65]
	v_bfe_u32 v180, v154, 4, 2
	v_lshlrev_b32_e32 v180, 3, v180
	v_mov_b32_e32 v181, 0
	v_lshl_add_u64 v[180:181], v[2:3], 0, v[180:181]
	v_cvt_pk_bf16_f32 v24, v24, v25
	v_cvt_pk_bf16_f32 v25, v26, v27
	v_lshlrev_b32_e32 v32, 16, v186
	v_and_b32_e32 v33, 0xffff0000, v186
	v_lshlrev_b32_e32 v34, 16, v187
	v_and_b32_e32 v35, 0xffff0000, v187
	v_mul_f32_e32 v36, 0xbfb8aa3b, v32
	v_mul_f32_e32 v37, 0xbfb8aa3b, v33
	v_mul_f32_e32 v38, 0xbfb8aa3b, v34
	v_mul_f32_e32 v39, 0xbfb8aa3b, v35
	v_exp_f32_e32 v36, v36
	v_exp_f32_e32 v37, v37
	v_exp_f32_e32 v38, v38
	v_exp_f32_e32 v39, v39
	v_pk_mul_f32 v[42:43], v[42:43], v[6:7] op_sel_hi:[1,0]
	v_pk_mul_f32 v[46:47], v[46:47], v[6:7] op_sel_hi:[1,0]
	v_pk_add_f32 v[36:37], v[36:37], 1.0 op_sel_hi:[1,0]
	v_pk_add_f32 v[38:39], v[38:39], 1.0 op_sel_hi:[1,0]
	v_pk_mul_f32 v[42:43], v[204:205], v[42:43]
	v_pk_mul_f32 v[46:47], v[206:207], v[46:47]
	v_rcp_f32_e32 v36, v36
	v_rcp_f32_e32 v37, v37
	v_rcp_f32_e32 v38, v38
	v_rcp_f32_e32 v39, v39
	v_pk_mul_f32 v[32:33], v[32:33], v[36:37]
	v_pk_mul_f32 v[34:35], v[34:35], v[38:39]
	v_pk_mul_f32 v[42:43], v[32:33], v[42:43]
	v_pk_mul_f32 v[46:47], v[34:35], v[46:47]
	v_cvt_pk_bf16_f32 v26, v42, v43
	v_cvt_pk_bf16_f32 v27, v46, v47
	s_nop 1
	v_permlane32_swap_b32_e32 v24, v26
	v_permlane32_swap_b32_e32 v25, v27
	s_nop 0
	v_permlane16_swap_b32_e32 v24, v26
	v_permlane16_swap_b32_e32 v25, v27
	global_store_dwordx4 v[180:181], v[24:27], off
	v_lshlrev_b32_e32 v172, 16, v188
	v_and_b32_e32 v173, 0xffff0000, v188
	v_lshlrev_b32_e32 v174, 16, v189
	v_and_b32_e32 v175, 0xffff0000, v189
	v_mul_f32_e32 v176, 0xbfb8aa3b, v172
	v_mul_f32_e32 v177, 0xbfb8aa3b, v173
	v_mul_f32_e32 v178, 0xbfb8aa3b, v174
	v_mul_f32_e32 v179, 0xbfb8aa3b, v175
	v_exp_f32_e32 v176, v176
	v_exp_f32_e32 v177, v177
	v_exp_f32_e32 v178, v178
	v_exp_f32_e32 v179, v179
	v_pk_mul_f32 v[84:85], v[84:85], v[6:7] op_sel_hi:[1,0]
	v_pk_mul_f32 v[88:89], v[88:89], v[6:7] op_sel_hi:[1,0]
	v_pk_add_f32 v[176:177], v[176:177], 1.0 op_sel_hi:[1,0]
	v_pk_add_f32 v[178:179], v[178:179], 1.0 op_sel_hi:[1,0]
	v_pk_mul_f32 v[84:85], v[208:209], v[84:85]
	v_pk_mul_f32 v[88:89], v[210:211], v[88:89]
	v_rcp_f32_e32 v176, v176
	v_rcp_f32_e32 v177, v177
	v_rcp_f32_e32 v178, v178
	v_rcp_f32_e32 v179, v179
	v_pk_mul_f32 v[172:173], v[172:173], v[176:177]
	v_pk_mul_f32 v[174:175], v[174:175], v[178:179]
	v_pk_mul_f32 v[84:85], v[172:173], v[84:85]
	v_pk_mul_f32 v[88:89], v[174:175], v[88:89]
	v_cvt_pk_bf16_f32 v160, v84, v85
	v_cvt_pk_bf16_f32 v161, v88, v89
	v_lshlrev_b32_e32 v32, 16, v190
	v_and_b32_e32 v33, 0xffff0000, v190
	v_lshlrev_b32_e32 v34, 16, v191
	v_and_b32_e32 v35, 0xffff0000, v191
	v_mul_f32_e32 v36, 0xbfb8aa3b, v32
	v_mul_f32_e32 v37, 0xbfb8aa3b, v33
	v_mul_f32_e32 v38, 0xbfb8aa3b, v34
	v_mul_f32_e32 v39, 0xbfb8aa3b, v35
	v_exp_f32_e32 v36, v36
	v_exp_f32_e32 v37, v37
	v_exp_f32_e32 v38, v38
	v_exp_f32_e32 v39, v39
	v_pk_mul_f32 v[22:23], v[22:23], v[6:7] op_sel_hi:[1,0]
	v_pk_mul_f32 v[20:21], v[20:21], v[6:7] op_sel_hi:[1,0]
	v_pk_add_f32 v[36:37], v[36:37], 1.0 op_sel_hi:[1,0]
	v_pk_add_f32 v[38:39], v[38:39], 1.0 op_sel_hi:[1,0]
	v_pk_mul_f32 v[22:23], v[212:213], v[22:23]
	v_pk_mul_f32 v[20:21], v[214:215], v[20:21]
	v_rcp_f32_e32 v36, v36
	v_rcp_f32_e32 v37, v37
	v_rcp_f32_e32 v38, v38
	v_rcp_f32_e32 v39, v39
	v_pk_mul_f32 v[32:33], v[32:33], v[36:37]
	v_pk_mul_f32 v[34:35], v[34:35], v[38:39]
	v_pk_mul_f32 v[22:23], v[32:33], v[22:23]
	v_pk_mul_f32 v[20:21], v[34:35], v[20:21]
	v_cvt_pk_bf16_f32 v162, v22, v23
	v_cvt_pk_bf16_f32 v163, v20, v21
	s_nop 1
	v_permlane32_swap_b32_e32 v160, v162
	v_permlane32_swap_b32_e32 v161, v163
	s_nop 0
	v_permlane16_swap_b32_e32 v160, v162
	v_permlane16_swap_b32_e32 v161, v163
	global_store_dwordx4 v[180:181], v[160:163], off offset:64
	v_lshlrev_b32_e32 v172, 16, v192
	v_and_b32_e32 v173, 0xffff0000, v192
	v_lshlrev_b32_e32 v174, 16, v193
	v_and_b32_e32 v175, 0xffff0000, v193
	v_mul_f32_e32 v176, 0xbfb8aa3b, v172
	v_mul_f32_e32 v177, 0xbfb8aa3b, v173
	v_mul_f32_e32 v178, 0xbfb8aa3b, v174
	v_mul_f32_e32 v179, 0xbfb8aa3b, v175
	v_exp_f32_e32 v176, v176
	v_exp_f32_e32 v177, v177
	v_exp_f32_e32 v178, v178
	v_exp_f32_e32 v179, v179
	v_pk_mul_f32 v[18:19], v[18:19], v[6:7] op_sel_hi:[1,0]
	v_pk_mul_f32 v[16:17], v[16:17], v[6:7] op_sel_hi:[1,0]
	v_pk_add_f32 v[176:177], v[176:177], 1.0 op_sel_hi:[1,0]
	v_pk_add_f32 v[178:179], v[178:179], 1.0 op_sel_hi:[1,0]
	v_pk_mul_f32 v[18:19], v[216:217], v[18:19]
	v_pk_mul_f32 v[16:17], v[218:219], v[16:17]
	v_rcp_f32_e32 v176, v176
	v_rcp_f32_e32 v177, v177
	v_rcp_f32_e32 v178, v178
	v_rcp_f32_e32 v179, v179
	v_pk_mul_f32 v[172:173], v[172:173], v[176:177]
	v_pk_mul_f32 v[174:175], v[174:175], v[178:179]
	v_pk_mul_f32 v[18:19], v[172:173], v[18:19]
	v_pk_mul_f32 v[16:17], v[174:175], v[16:17]
	v_cvt_pk_bf16_f32 v164, v18, v19
	v_cvt_pk_bf16_f32 v165, v16, v17
	v_lshlrev_b32_e32 v32, 16, v194
	v_and_b32_e32 v33, 0xffff0000, v194
	v_lshlrev_b32_e32 v34, 16, v195
	v_and_b32_e32 v35, 0xffff0000, v195
	v_mul_f32_e32 v36, 0xbfb8aa3b, v32
	v_mul_f32_e32 v37, 0xbfb8aa3b, v33
	v_mul_f32_e32 v38, 0xbfb8aa3b, v34
	v_mul_f32_e32 v39, 0xbfb8aa3b, v35
	v_exp_f32_e32 v36, v36
	v_exp_f32_e32 v37, v37
	v_exp_f32_e32 v38, v38
	v_exp_f32_e32 v39, v39
	v_pk_mul_f32 v[14:15], v[14:15], v[6:7] op_sel_hi:[1,0]
	v_pk_mul_f32 v[12:13], v[12:13], v[6:7] op_sel_hi:[1,0]
	v_pk_add_f32 v[36:37], v[36:37], 1.0 op_sel_hi:[1,0]
	v_pk_add_f32 v[38:39], v[38:39], 1.0 op_sel_hi:[1,0]
	v_pk_mul_f32 v[14:15], v[220:221], v[14:15]
	v_pk_mul_f32 v[12:13], v[222:223], v[12:13]
	v_rcp_f32_e32 v36, v36
	v_rcp_f32_e32 v37, v37
	v_rcp_f32_e32 v38, v38
	v_rcp_f32_e32 v39, v39
	v_pk_mul_f32 v[32:33], v[32:33], v[36:37]
	v_pk_mul_f32 v[34:35], v[34:35], v[38:39]
	v_pk_mul_f32 v[14:15], v[32:33], v[14:15]
	v_pk_mul_f32 v[12:13], v[34:35], v[12:13]
	v_cvt_pk_bf16_f32 v166, v14, v15
	v_cvt_pk_bf16_f32 v167, v12, v13
	s_nop 1
	v_permlane32_swap_b32_e32 v164, v166
	v_permlane32_swap_b32_e32 v165, v167
	s_nop 0
	v_permlane16_swap_b32_e32 v164, v166
	v_permlane16_swap_b32_e32 v165, v167
	global_store_dwordx4 v[180:181], v[164:167], off offset:128
	v_lshlrev_b32_e32 v172, 16, v196
	v_and_b32_e32 v173, 0xffff0000, v196
	v_lshlrev_b32_e32 v174, 16, v197
	v_and_b32_e32 v175, 0xffff0000, v197
	v_mul_f32_e32 v176, 0xbfb8aa3b, v172
	v_mul_f32_e32 v177, 0xbfb8aa3b, v173
	v_mul_f32_e32 v178, 0xbfb8aa3b, v174
	v_mul_f32_e32 v179, 0xbfb8aa3b, v175
	v_exp_f32_e32 v176, v176
	v_exp_f32_e32 v177, v177
	v_exp_f32_e32 v178, v178
	v_exp_f32_e32 v179, v179
	v_pk_mul_f32 v[10:11], v[10:11], v[6:7] op_sel_hi:[1,0]
	v_pk_mul_f32 v[8:9], v[8:9], v[6:7] op_sel_hi:[1,0]
	v_pk_add_f32 v[176:177], v[176:177], 1.0 op_sel_hi:[1,0]
	v_pk_add_f32 v[178:179], v[178:179], 1.0 op_sel_hi:[1,0]
	v_pk_mul_f32 v[10:11], v[224:225], v[10:11]
	v_pk_mul_f32 v[8:9], v[226:227], v[8:9]
	v_rcp_f32_e32 v176, v176
	v_rcp_f32_e32 v177, v177
	v_rcp_f32_e32 v178, v178
	v_rcp_f32_e32 v179, v179
	v_pk_mul_f32 v[172:173], v[172:173], v[176:177]
	v_pk_mul_f32 v[174:175], v[174:175], v[178:179]
	v_pk_mul_f32 v[10:11], v[172:173], v[10:11]
	v_pk_mul_f32 v[8:9], v[174:175], v[8:9]
	v_cvt_pk_bf16_f32 v168, v10, v11
	v_cvt_pk_bf16_f32 v169, v8, v9
	v_lshlrev_b32_e32 v32, 16, v198
	v_and_b32_e32 v33, 0xffff0000, v198
	v_lshlrev_b32_e32 v34, 16, v199
	v_and_b32_e32 v35, 0xffff0000, v199
	v_mul_f32_e32 v36, 0xbfb8aa3b, v32
	v_mul_f32_e32 v37, 0xbfb8aa3b, v33
	v_mul_f32_e32 v38, 0xbfb8aa3b, v34
	v_mul_f32_e32 v39, 0xbfb8aa3b, v35
	v_exp_f32_e32 v36, v36
	v_exp_f32_e32 v37, v37
	v_exp_f32_e32 v38, v38
	v_exp_f32_e32 v39, v39
	v_pk_mul_f32 v[4:5], v[4:5], v[6:7] op_sel_hi:[1,0]
	v_pk_mul_f32 v[0:1], v[0:1], v[6:7] op_sel_hi:[1,0]
	v_pk_add_f32 v[36:37], v[36:37], 1.0 op_sel_hi:[1,0]
	v_pk_add_f32 v[38:39], v[38:39], 1.0 op_sel_hi:[1,0]
	v_pk_mul_f32 v[4:5], v[228:229], v[4:5]
	v_pk_mul_f32 v[0:1], v[230:231], v[0:1]
	v_rcp_f32_e32 v36, v36
	v_rcp_f32_e32 v37, v37
	v_rcp_f32_e32 v38, v38
	v_rcp_f32_e32 v39, v39
	v_pk_mul_f32 v[32:33], v[32:33], v[36:37]
	v_pk_mul_f32 v[34:35], v[34:35], v[38:39]
	v_pk_mul_f32 v[4:5], v[32:33], v[4:5]
	v_pk_mul_f32 v[0:1], v[34:35], v[0:1]
	v_cvt_pk_bf16_f32 v170, v4, v5
	v_cvt_pk_bf16_f32 v171, v0, v1
	s_nop 1
	v_permlane32_swap_b32_e32 v168, v170
	v_permlane32_swap_b32_e32 v169, v171
	s_nop 0
	v_permlane16_swap_b32_e32 v168, v170
	v_permlane16_swap_b32_e32 v169, v171
	global_store_dwordx4 v[180:181], v[168:171], off offset:192
	s_waitcnt lgkmcnt(0)
	s_barrier
	s_cbranch_scc1 .LBB0_495
